# v68_a3_bcum_dot_on_f32_mfma
# speedup vs baseline: 1.0012x; 1.0012x over previous
; #define LAS __attribute__((address_space(3)))
; __device__ __forceinline__ void gla_bcum(KArgs a, int tid, int t0, int h, LAS float* segtot, LAS float* glrs, float (&bc)[32], float& tot) {
;     const int d = tid & 127, seg = __builtin_amdgcn_readfirstlane(tid >> 7), col = h * 128 + d;
;     const float* glr = (const float*)(a->ws + WS_GLR);
;     float w2r[16];
; #pragma unroll
;     for (int j = 0; j < 16; ++j) w2r[j] = a->gate_w2[j * 512 + col];
;     const float bias = a->gate_b[col];
;     *(LAS f32x4*)(glrs + tid * 4) = *(const f32x4*)(glr + (size_t)t0 * 16 + tid * 4);
;     __syncthreads();
;     float run = 0.f;
; #pragma unroll
;     for (int r = 0; r < 32; ++r) { const LAS f32x4* gp = (const LAS f32x4*)(glrs + (seg * 32 + r) * 16);
;         float z = bias;
; #pragma unroll
;         for (int q = 0; q < 4; ++q) { const f32x4 g = gp[q]; z += g[0] * w2r[4 * q] + g[1] * w2r[4 * q + 1] + g[2] * w2r[4 * q + 2] + g[3] * w2r[4 * q + 3]; }
;         const float la = (fminf(z, 0.f) - __logf(1.0f + __expf(-fabsf(z)))) * (1.0f / 16.0f);
;         run += la; bc[r] = run; }
.LBB0_478:
	s_bfe_u32 s1, s42, 0x20005
	s_lshl_b32 s8, s1, 9
	v_lshl_or_b32 v0, v88, 2, s8
	s_and_b32 s0, s42, 31
	s_nop 0
	s_lshl_b32 s6, s42, 5
	s_nop 0
	s_and_b32 s6, s6, 0xfffff000
	s_lshl_b32 s7, s0, 7
	s_or_b32 s44, s6, s7
	s_ashr_i32 s45, s44, 31
	s_nop 0
	s_lshl_b64 s[6:7], s[44:45], 6
	v_lshl_add_u64 v[6:7], v[90:91], 0, s[6:7]
	s_nop 0
	s_barrier
	global_load_dwordx4 v[20:23], v[6:7], off
	v_and_b32_e32 v250, 31, v88
	v_and_b32_e32 v251, 64, v88
	v_or_b32_e32 v250, v250, v251
	v_bfe_u32 v251, v88, 5, 1
	v_lshlrev_b32_e32 v250, 2, v250
	v_lshl_add_u32 v250, v251, 11, v250
	v_add_u32_e32 v250, s8, v250
	global_load_dword v61, v250, s[16:17]
	global_load_dword v62, v250, s[16:17] offset:128
	v_add_u32_e32 v250, 0x1000, v250
	global_load_dword v63, v250, s[16:17]
	global_load_dword v64, v250, s[16:17] offset:128
	v_add_u32_e32 v250, 0x1000, v250
	global_load_dword v65, v250, s[16:17]
	global_load_dword v66, v250, s[16:17] offset:128
	v_add_u32_e32 v250, 0x1000, v250
	global_load_dword v67, v250, s[16:17]
	global_load_dword v68, v250, s[16:17] offset:128
	v_add_u32_e32 v250, 0x1000, v250
	global_load_dword v69, v250, s[16:17]
	global_load_dword v70, v250, s[16:17] offset:128
	v_add_u32_e32 v250, 0x1000, v250
	global_load_dword v71, v250, s[16:17]
	global_load_dword v72, v250, s[16:17] offset:128
	v_add_u32_e32 v250, 0x1000, v250
	global_load_dword v73, v250, s[16:17]
	global_load_dword v74, v250, s[16:17] offset:128
	v_add_u32_e32 v250, 0x1000, v250
	global_load_dword v75, v250, s[16:17]
	global_load_dword v76, v250, s[16:17] offset:128
	s_nop 0
	s_nop 0
	v_readfirstlane_b32 s36, v84
	s_nop 0
	s_ashr_i32 s9, s36, 7
	s_nop 0
	s_nop 0
	global_load_dword v19, v0, s[18:19]
	s_lshl_b32 s98, s1, 8
	s_mov_b32 s99, 0
	v_lshl_add_u64 v[82:83], v[92:93], 0, s[98:99]
	s_lshl_b32 s6, s9, 11
	s_add_i32 s6, s6, 0
	s_add_i32 s6, s6, 0x11000
	v_mov_b32_e32 v0, s6
	v_mov_b32_e32 v111, v1
	s_waitcnt vmcnt(17)
	ds_write_b128 v117, v[20:23]
	s_waitcnt lgkmcnt(0)
	s_barrier
	v_and_b32_e32 v250, 63, v186
	v_and_b32_e32 v251, 31, v250
	v_lshrrev_b32_e32 v252, 5, v250
	v_lshlrev_b32_e32 v253, 6, v251
	v_lshl_add_u32 v253, v252, 2, v253
	v_add_u32_e32 v253, v0, v253
	ds_read_b32 v242, v253
	ds_read_b32 v243, v253 offset:8
	ds_read_b32 v244, v253 offset:16
	ds_read_b32 v245, v253 offset:24
	ds_read_b32 v246, v253 offset:32
	ds_read_b32 v247, v253 offset:40
	ds_read_b32 v248, v253 offset:48
	ds_read_b32 v249, v253 offset:56
	s_waitcnt lgkmcnt(0)
	s_waitcnt vmcnt(16)
	v_mfma_f32_32x32x2_f32 v[210:225], v242, v61, 0
	s_waitcnt vmcnt(15)
	v_mfma_f32_32x32x2_f32 v[226:241], v242, v62, 0
	s_waitcnt vmcnt(14)
	v_mfma_f32_32x32x2_f32 v[210:225], v243, v63, v[210:225]
	s_waitcnt vmcnt(13)
	v_mfma_f32_32x32x2_f32 v[226:241], v243, v64, v[226:241]
	s_waitcnt vmcnt(12)
	v_mfma_f32_32x32x2_f32 v[210:225], v244, v65, v[210:225]
	s_waitcnt vmcnt(11)
	v_mfma_f32_32x32x2_f32 v[226:241], v244, v66, v[226:241]
	s_waitcnt vmcnt(10)
	v_mfma_f32_32x32x2_f32 v[210:225], v245, v67, v[210:225]
	s_waitcnt vmcnt(9)
	v_mfma_f32_32x32x2_f32 v[226:241], v245, v68, v[226:241]
	s_waitcnt vmcnt(8)
	v_mfma_f32_32x32x2_f32 v[210:225], v246, v69, v[210:225]
	s_waitcnt vmcnt(7)
	v_mfma_f32_32x32x2_f32 v[226:241], v246, v70, v[226:241]
	s_waitcnt vmcnt(6)
	v_mfma_f32_32x32x2_f32 v[210:225], v247, v71, v[210:225]
	s_waitcnt vmcnt(5)
	v_mfma_f32_32x32x2_f32 v[226:241], v247, v72, v[226:241]
	s_waitcnt vmcnt(4)
	v_mfma_f32_32x32x2_f32 v[210:225], v248, v73, v[210:225]
	s_waitcnt vmcnt(3)
	v_mfma_f32_32x32x2_f32 v[226:241], v248, v74, v[226:241]
	s_waitcnt vmcnt(2)
	v_mfma_f32_32x32x2_f32 v[210:225], v249, v75, v[210:225]
	s_waitcnt vmcnt(1)
	v_mfma_f32_32x32x2_f32 v[226:241], v249, v76, v[226:241]
	s_nop 15
	s_nop 3
	v_permlane32_swap_b32_e32 v210, v226
	v_permlane32_swap_b32_e32 v211, v227
	v_permlane32_swap_b32_e32 v212, v228
	v_permlane32_swap_b32_e32 v213, v229
	v_permlane32_swap_b32_e32 v214, v230
	v_permlane32_swap_b32_e32 v215, v231
	v_permlane32_swap_b32_e32 v216, v232
	v_permlane32_swap_b32_e32 v217, v233
	v_permlane32_swap_b32_e32 v218, v234
	v_permlane32_swap_b32_e32 v219, v235
	v_permlane32_swap_b32_e32 v220, v236
	v_permlane32_swap_b32_e32 v221, v237
	v_permlane32_swap_b32_e32 v222, v238
	v_permlane32_swap_b32_e32 v223, v239
	v_permlane32_swap_b32_e32 v224, v240
	v_permlane32_swap_b32_e32 v225, v241
	s_waitcnt vmcnt(0)
; #define LAS __attribute__((address_space(3)))
; __device__ __forceinline__ void gla_bcum(KArgs a, int tid, int t0, int h, LAS float* segtot, LAS float* glrs, float (&bc)[32], float& tot) {
;     ...
;     for (int r = 0; r < 32; ++r) { const LAS f32x4* gp = (const LAS f32x4*)(glrs + (seg * 32 + r) * 16);
;         float z = bias;
; #pragma unroll
;         for (int q = 0; q < 4; ++q) { const f32x4 g = gp[q]; z += g[0] * w2r[4 * q] + g[1] * w2r[4 * q + 1] + g[2] * w2r[4 * q + 2] + g[3] * w2r[4 * q + 3]; }
;         const float la = (fminf(z, 0.f) - __logf(1.0f + __expf(-fabsf(z)))) * (1.0f / 16.0f);
;         run += la; bc[r] = run; }
	v_add_f32_e32 v210, v19, v210
	v_add_f32_e32 v226, v19, v226
	v_add_f32_e32 v211, v19, v211
	v_add_f32_e32 v227, v19, v227
	v_add_f32_e32 v212, v19, v212
	v_add_f32_e32 v228, v19, v228
	v_add_f32_e32 v213, v19, v213
	v_add_f32_e32 v229, v19, v229
	v_add_f32_e32 v214, v19, v214
	v_add_f32_e32 v230, v19, v230
	v_add_f32_e32 v215, v19, v215
	v_add_f32_e32 v231, v19, v231
	v_add_f32_e32 v216, v19, v216
	v_add_f32_e32 v232, v19, v232
	v_add_f32_e32 v217, v19, v217
	v_add_f32_e32 v233, v19, v233
	v_add_f32_e32 v218, v19, v218
	v_add_f32_e32 v234, v19, v234
	v_add_f32_e32 v219, v19, v219
	v_add_f32_e32 v235, v19, v235
	v_add_f32_e32 v220, v19, v220
	v_add_f32_e32 v236, v19, v236
	v_add_f32_e32 v221, v19, v221
	v_add_f32_e32 v237, v19, v237
	v_add_f32_e32 v222, v19, v222
	v_add_f32_e32 v238, v19, v238
	v_add_f32_e32 v223, v19, v223
	v_add_f32_e32 v239, v19, v239
	v_add_f32_e32 v224, v19, v224
	v_add_f32_e32 v240, v19, v240
	v_add_f32_e32 v225, v19, v225
	v_add_f32_e32 v241, v19, v241
	v_mul_f32_e64 v20, |v210|, s33
	v_exp_f32_e32 v20, v20
	s_nop 0
	v_add_f32_e32 v20, 1.0, v20
	v_log_f32_e32 v28, v20
	s_nop 0
	v_mul_f32_e32 v20, 0x3f317217, v28
	v_fma_f32 v29, v28, s35, -v20
	v_fmac_f32_e32 v29, 0x3377d1cf, v28
	v_mul_f32_e64 v21, |v211|, s33
	v_exp_f32_e32 v21, v21
	v_fmac_f32_e32 v29, 0x3f317217, v28
	v_add_f32_e32 v21, 1.0, v21
	v_mov_b32_e32 v22, v29
	v_min_f32_e32 v18, 0, v210
	v_log_f32_e32 v28, v21
	v_sub_f32_e32 v18, v18, v22
	v_min_f32_e32 v29, 0, v211
	v_mul_f32_e32 v24, 0x3f317217, v28
	v_fma_f32 v30, v28, s35, -v24
	v_fmac_f32_e32 v30, 0x3377d1cf, v28
	v_mul_f32_e64 v20, |v212|, s33
	v_exp_f32_e32 v20, v20
	v_fmac_f32_e32 v30, 0x3f317217, v28
	v_add_f32_e32 v20, 1.0, v20
	v_mov_b32_e32 v22, v30
	v_min_f32_e32 v21, 0, v212
	v_log_f32_e32 v30, v20
	v_sub_f32_e32 v20, v29, v22
	v_fma_f32 v18, v18, s47, 0
	v_mul_f32_e32 v26, 0x3f317217, v30
	v_fma_f32 v31, v30, s35, -v26
	v_mul_f32_e64 v23, |v213|, s33
	v_exp_f32_e32 v23, v23
	v_fmac_f32_e32 v31, 0x3377d1cf, v30
	v_fmac_f32_e32 v31, 0x3f317217, v30
	v_add_f32_e32 v23, 1.0, v23
	v_mov_b32_e32 v24, v31
	v_sub_f32_e32 v21, v21, v24
	v_log_f32_e32 v30, v23
	v_min_f32_e32 v31, 0, v213
	v_fmamk_f32 v20, v20, 0x3d800000, v18
	v_mul_f32_e32 v26, 0x3f317217, v30
	v_fma_f32 v32, v30, s35, -v26
	v_mul_f32_e64 v22, |v226|, s33
	v_exp_f32_e32 v22, v22
	v_fmac_f32_e32 v32, 0x3377d1cf, v30
	v_fmac_f32_e32 v32, 0x3f317217, v30
	v_add_f32_e32 v22, 1.0, v22
	v_mov_b32_e32 v24, v32
	v_min_f32_e32 v23, 0, v226
	v_log_f32_e32 v32, v22
	v_sub_f32_e32 v22, v31, v24
	v_fmamk_f32 v21, v21, 0x3d800000, v20
	v_mul_f32_e32 v28, 0x3f317217, v32
	v_fma_f32 v33, v32, s35, -v28
	v_mul_f32_e64 v25, |v227|, s33
	v_exp_f32_e32 v25, v25
	v_fmac_f32_e32 v33, 0x3377d1cf, v32
	v_fmac_f32_e32 v33, 0x3f317217, v32
	v_add_f32_e32 v25, 1.0, v25
	v_mov_b32_e32 v26, v33
	v_sub_f32_e32 v23, v23, v26
	v_log_f32_e32 v32, v25
	v_min_f32_e32 v33, 0, v227
	v_fmamk_f32 v22, v22, 0x3d800000, v21
	v_mul_f32_e32 v28, 0x3f317217, v32
	v_fma_f32 v34, v32, s35, -v28
	v_mul_f32_e64 v24, |v228|, s33
	v_exp_f32_e32 v24, v24
	v_fmac_f32_e32 v34, 0x3377d1cf, v32
	v_fmac_f32_e32 v34, 0x3f317217, v32
	v_add_f32_e32 v24, 1.0, v24
	v_mov_b32_e32 v26, v34
	v_min_f32_e32 v25, 0, v228
	v_log_f32_e32 v34, v24
	v_sub_f32_e32 v24, v33, v26
	v_fmamk_f32 v23, v23, 0x3d800000, v22
	v_mul_f32_e32 v30, 0x3f317217, v34
	v_fma_f32 v35, v34, s35, -v30
	v_mul_f32_e64 v27, |v229|, s33
	v_exp_f32_e32 v27, v27
	v_fmac_f32_e32 v35, 0x3377d1cf, v34
	v_fmac_f32_e32 v35, 0x3f317217, v34
	v_add_f32_e32 v27, 1.0, v27
	v_mov_b32_e32 v28, v35
	v_sub_f32_e32 v25, v25, v28
	v_log_f32_e32 v34, v27
	v_min_f32_e32 v35, 0, v229
	v_fmamk_f32 v24, v24, 0x3d800000, v23
	v_mul_f32_e32 v30, 0x3f317217, v34
	v_fma_f32 v36, v34, s35, -v30
	v_mul_f32_e64 v26, |v214|, s33
	v_exp_f32_e32 v26, v26
	v_fmac_f32_e32 v36, 0x3377d1cf, v34
	v_fmac_f32_e32 v36, 0x3f317217, v34
	v_add_f32_e32 v26, 1.0, v26
	v_mov_b32_e32 v28, v36
	v_min_f32_e32 v27, 0, v214
	v_log_f32_e32 v36, v26
	v_sub_f32_e32 v26, v35, v28
	v_fmamk_f32 v25, v25, 0x3d800000, v24
	v_mul_f32_e32 v32, 0x3f317217, v36
	v_fma_f32 v37, v36, s35, -v32
	v_mul_f32_e64 v29, |v215|, s33
	v_exp_f32_e32 v29, v29
	v_fmac_f32_e32 v37, 0x3377d1cf, v36
	v_fmac_f32_e32 v37, 0x3f317217, v36
	v_add_f32_e32 v29, 1.0, v29
	v_mov_b32_e32 v30, v37
	v_sub_f32_e32 v27, v27, v30
	v_log_f32_e32 v36, v29
	v_min_f32_e32 v37, 0, v215
	v_fmamk_f32 v26, v26, 0x3d800000, v25
	v_mul_f32_e32 v32, 0x3f317217, v36
	v_fma_f32 v38, v36, s35, -v32
	v_mul_f32_e64 v28, |v216|, s33
	v_exp_f32_e32 v28, v28
	v_fmac_f32_e32 v38, 0x3377d1cf, v36
	v_fmac_f32_e32 v38, 0x3f317217, v36
	v_add_f32_e32 v28, 1.0, v28
	v_mov_b32_e32 v30, v38
	v_min_f32_e32 v29, 0, v216
	v_log_f32_e32 v38, v28
	v_sub_f32_e32 v28, v37, v30
	v_fmamk_f32 v27, v27, 0x3d800000, v26
	v_mul_f32_e32 v34, 0x3f317217, v38
	v_fma_f32 v39, v38, s35, -v34
	v_mul_f32_e64 v31, |v217|, s33
	v_exp_f32_e32 v31, v31
	v_fmac_f32_e32 v39, 0x3377d1cf, v38
	v_fmac_f32_e32 v39, 0x3f317217, v38
	v_add_f32_e32 v31, 1.0, v31
	v_mov_b32_e32 v32, v39
	v_sub_f32_e32 v29, v29, v32
	v_log_f32_e32 v38, v31
	v_min_f32_e32 v39, 0, v217
	v_fmamk_f32 v28, v28, 0x3d800000, v27
	v_mul_f32_e32 v34, 0x3f317217, v38
	v_fma_f32 v40, v38, s35, -v34
	v_mul_f32_e64 v30, |v230|, s33
	v_exp_f32_e32 v30, v30
	v_fmac_f32_e32 v40, 0x3377d1cf, v38
	v_fmac_f32_e32 v40, 0x3f317217, v38
	v_add_f32_e32 v30, 1.0, v30
	v_mov_b32_e32 v32, v40
	v_min_f32_e32 v31, 0, v230
	v_log_f32_e32 v40, v30
	v_sub_f32_e32 v30, v39, v32
	v_fmamk_f32 v29, v29, 0x3d800000, v28
	v_mul_f32_e32 v36, 0x3f317217, v40
	v_fma_f32 v41, v40, s35, -v36
	v_mul_f32_e64 v33, |v231|, s33
; #define LAS __attribute__((address_space(3)))
; __device__ __forceinline__ void gla_bcum(KArgs a, int tid, int t0, int h, LAS float* segtot, LAS float* glrs, float (&bc)[32], float& tot) {
;     ...
;     for (int r = 0; r < 32; ++r) { const LAS f32x4* gp = (const LAS f32x4*)(glrs + (seg * 32 + r) * 16);
;         float z = bias;
; #pragma unroll
;         for (int q = 0; q < 4; ++q) { const f32x4 g = gp[q]; z += g[0] * w2r[4 * q] + g[1] * w2r[4 * q + 1] + g[2] * w2r[4 * q + 2] + g[3] * w2r[4 * q + 3]; }
;         const float la = (fminf(z, 0.f) - __logf(1.0f + __expf(-fabsf(z)))) * (1.0f / 16.0f);
;         run += la; bc[r] = run; }
	v_exp_f32_e32 v33, v33
	v_fmac_f32_e32 v41, 0x3377d1cf, v40
	v_fmac_f32_e32 v41, 0x3f317217, v40
	v_add_f32_e32 v33, 1.0, v33
	v_mov_b32_e32 v34, v41
	v_sub_f32_e32 v31, v31, v34
	v_log_f32_e32 v40, v33
	v_min_f32_e32 v41, 0, v231
	v_fmamk_f32 v30, v30, 0x3d800000, v29
	v_mul_f32_e32 v36, 0x3f317217, v40
	v_fma_f32 v42, v40, s35, -v36
	v_mul_f32_e64 v32, |v232|, s33
	v_exp_f32_e32 v32, v32
	v_fmac_f32_e32 v42, 0x3377d1cf, v40
	v_fmac_f32_e32 v42, 0x3f317217, v40
	v_add_f32_e32 v32, 1.0, v32
	v_mov_b32_e32 v34, v42
	v_min_f32_e32 v33, 0, v232
	v_log_f32_e32 v42, v32
	v_sub_f32_e32 v32, v41, v34
	v_fmamk_f32 v31, v31, 0x3d800000, v30
	v_mul_f32_e32 v38, 0x3f317217, v42
	v_fma_f32 v43, v42, s35, -v38
	v_mul_f32_e64 v35, |v233|, s33
	v_exp_f32_e32 v35, v35
	v_fmac_f32_e32 v43, 0x3377d1cf, v42
	v_fmac_f32_e32 v43, 0x3f317217, v42
	v_add_f32_e32 v35, 1.0, v35
	v_mov_b32_e32 v36, v43
	v_sub_f32_e32 v33, v33, v36
	v_log_f32_e32 v42, v35
	v_min_f32_e32 v43, 0, v233
	v_fmamk_f32 v32, v32, 0x3d800000, v31
	v_mul_f32_e32 v38, 0x3f317217, v42
	v_fma_f32 v44, v42, s35, -v38
	v_mul_f32_e64 v34, |v218|, s33
	v_exp_f32_e32 v34, v34
	v_fmac_f32_e32 v44, 0x3377d1cf, v42
	v_fmac_f32_e32 v44, 0x3f317217, v42
	v_add_f32_e32 v34, 1.0, v34
	v_mov_b32_e32 v36, v44
	v_min_f32_e32 v35, 0, v218
	v_log_f32_e32 v44, v34
	v_sub_f32_e32 v34, v43, v36
	v_fmamk_f32 v33, v33, 0x3d800000, v32
	v_mul_f32_e32 v40, 0x3f317217, v44
	v_fma_f32 v45, v44, s35, -v40
	v_mul_f32_e64 v37, |v219|, s33
	v_exp_f32_e32 v37, v37
	v_fmac_f32_e32 v45, 0x3377d1cf, v44
	v_fmac_f32_e32 v45, 0x3f317217, v44
	v_add_f32_e32 v37, 1.0, v37
	v_mov_b32_e32 v38, v45
	v_sub_f32_e32 v35, v35, v38
	v_log_f32_e32 v44, v37
	v_min_f32_e32 v45, 0, v219
	v_fmamk_f32 v34, v34, 0x3d800000, v33
	v_mul_f32_e32 v40, 0x3f317217, v44
	v_fma_f32 v46, v44, s35, -v40
	v_mul_f32_e64 v36, |v220|, s33
	v_exp_f32_e32 v36, v36
	v_fmac_f32_e32 v46, 0x3377d1cf, v44
	v_fmac_f32_e32 v46, 0x3f317217, v44
	v_add_f32_e32 v36, 1.0, v36
	v_mov_b32_e32 v38, v46
	v_min_f32_e32 v37, 0, v220
	v_log_f32_e32 v46, v36
	v_sub_f32_e32 v36, v45, v38
	v_fmamk_f32 v35, v35, 0x3d800000, v34
	v_mul_f32_e32 v42, 0x3f317217, v46
	v_fma_f32 v47, v46, s35, -v42
	v_mul_f32_e64 v39, |v221|, s33
	v_exp_f32_e32 v39, v39
	v_fmac_f32_e32 v47, 0x3377d1cf, v46
	v_fmac_f32_e32 v47, 0x3f317217, v46
	v_add_f32_e32 v39, 1.0, v39
	v_mov_b32_e32 v40, v47
	v_sub_f32_e32 v37, v37, v40
	v_log_f32_e32 v46, v39
	v_min_f32_e32 v47, 0, v221
	v_fmamk_f32 v36, v36, 0x3d800000, v35
	v_mul_f32_e32 v42, 0x3f317217, v46
	v_fma_f32 v48, v46, s35, -v42
	v_mul_f32_e64 v38, |v234|, s33
	v_exp_f32_e32 v38, v38
	v_fmac_f32_e32 v48, 0x3377d1cf, v46
	v_fmac_f32_e32 v48, 0x3f317217, v46
	v_add_f32_e32 v38, 1.0, v38
	v_mov_b32_e32 v40, v48
	v_min_f32_e32 v39, 0, v234
	v_log_f32_e32 v48, v38
	v_sub_f32_e32 v38, v47, v40
	v_fmamk_f32 v37, v37, 0x3d800000, v36
	v_mul_f32_e32 v44, 0x3f317217, v48
	v_fma_f32 v49, v48, s35, -v44
	v_mul_f32_e64 v41, |v235|, s33
	v_exp_f32_e32 v41, v41
	v_fmac_f32_e32 v49, 0x3377d1cf, v48
	v_fmac_f32_e32 v49, 0x3f317217, v48
	v_add_f32_e32 v41, 1.0, v41
	v_mov_b32_e32 v42, v49
	v_sub_f32_e32 v39, v39, v42
	v_log_f32_e32 v48, v41
	v_min_f32_e32 v49, 0, v235
	v_fmamk_f32 v38, v38, 0x3d800000, v37
	v_mul_f32_e32 v44, 0x3f317217, v48
	v_fma_f32 v50, v48, s35, -v44
	v_mul_f32_e64 v40, |v236|, s33
	v_exp_f32_e32 v40, v40
	v_fmac_f32_e32 v50, 0x3377d1cf, v48
	v_fmac_f32_e32 v50, 0x3f317217, v48
	v_add_f32_e32 v40, 1.0, v40
	v_mov_b32_e32 v42, v50
	v_min_f32_e32 v41, 0, v236
	v_log_f32_e32 v50, v40
	v_sub_f32_e32 v40, v49, v42
	v_fmamk_f32 v39, v39, 0x3d800000, v38
	v_mul_f32_e32 v46, 0x3f317217, v50
	v_fma_f32 v51, v50, s35, -v46
	v_mul_f32_e64 v43, |v237|, s33
	v_exp_f32_e32 v43, v43
	v_fmac_f32_e32 v51, 0x3377d1cf, v50
	v_fmac_f32_e32 v51, 0x3f317217, v50
	v_add_f32_e32 v43, 1.0, v43
	v_mov_b32_e32 v44, v51
	v_sub_f32_e32 v41, v41, v44
	v_log_f32_e32 v50, v43
	v_min_f32_e32 v51, 0, v237
	v_fmamk_f32 v40, v40, 0x3d800000, v39
	v_mul_f32_e32 v46, 0x3f317217, v50
	v_fma_f32 v52, v50, s35, -v46
	v_mul_f32_e64 v42, |v222|, s33
	v_exp_f32_e32 v42, v42
	v_fmac_f32_e32 v52, 0x3377d1cf, v50
	v_fmac_f32_e32 v52, 0x3f317217, v50
	v_add_f32_e32 v42, 1.0, v42
	v_mov_b32_e32 v44, v52
	v_min_f32_e32 v43, 0, v222
	v_log_f32_e32 v52, v42
	v_sub_f32_e32 v42, v51, v44
	v_fmamk_f32 v41, v41, 0x3d800000, v40
	v_mul_f32_e32 v48, 0x3f317217, v52
	v_fma_f32 v53, v52, s35, -v48
	v_mul_f32_e64 v45, |v223|, s33
	v_exp_f32_e32 v45, v45
	v_fmac_f32_e32 v53, 0x3377d1cf, v52
	v_fmac_f32_e32 v53, 0x3f317217, v52
	v_add_f32_e32 v45, 1.0, v45
	v_mov_b32_e32 v46, v53
	v_sub_f32_e32 v43, v43, v46
	v_log_f32_e32 v52, v45
	v_min_f32_e32 v53, 0, v223
	v_fmamk_f32 v42, v42, 0x3d800000, v41
	v_mul_f32_e32 v48, 0x3f317217, v52
	v_fma_f32 v54, v52, s35, -v48
	v_mul_f32_e64 v44, |v224|, s33
	v_exp_f32_e32 v44, v44
	v_fmac_f32_e32 v54, 0x3377d1cf, v52
	v_fmac_f32_e32 v54, 0x3f317217, v52
	v_add_f32_e32 v44, 1.0, v44
	v_mov_b32_e32 v46, v54
	v_min_f32_e32 v45, 0, v224
	v_log_f32_e32 v54, v44
	v_sub_f32_e32 v44, v53, v46
	v_fmamk_f32 v43, v43, 0x3d800000, v42
	v_mul_f32_e32 v50, 0x3f317217, v54
	v_fma_f32 v55, v54, s35, -v50
	v_mul_f32_e64 v47, |v225|, s33
	v_exp_f32_e32 v47, v47
	v_fmac_f32_e32 v55, 0x3377d1cf, v54
	v_fmac_f32_e32 v55, 0x3f317217, v54
	v_add_f32_e32 v47, 1.0, v47
	v_mov_b32_e32 v48, v55
	v_sub_f32_e32 v45, v45, v48
	v_log_f32_e32 v54, v47
	v_min_f32_e32 v55, 0, v225
	v_fmamk_f32 v44, v44, 0x3d800000, v43
	v_mul_f32_e32 v50, 0x3f317217, v54
	v_fma_f32 v56, v54, s35, -v50
	v_mul_f32_e64 v47, |v238|, s33
	v_exp_f32_e32 v47, v47
	v_fmac_f32_e32 v56, 0x3377d1cf, v54
	v_fmac_f32_e32 v56, 0x3f317217, v54
; #define LAS __attribute__((address_space(3)))
; __device__ __forceinline__ float bf2f(bf16_t v) { return __uint_as_float((unsigned)v << 16); }
; __device__ __forceinline__ unsigned f2bf(float f) { return (unsigned)__builtin_bit_cast(unsigned short, (__bf16)f); }
; __device__ __forceinline__ void gla_bcum(KArgs a, int tid, int t0, int h, LAS float* segtot, LAS float* glrs, float (&bc)[32], float& tot) {
;     ...
;     for (int r = 0; r < 32; ++r) { const LAS f32x4* gp = (const LAS f32x4*)(glrs + (seg * 32 + r) * 16);
;         float z = bias;
; #pragma unroll
;         for (int q = 0; q < 4; ++q) { const f32x4 g = gp[q]; z += g[0] * w2r[4 * q] + g[1] * w2r[4 * q + 1] + g[2] * w2r[4 * q + 2] + g[3] * w2r[4 * q + 3]; }
;         const float la = (fminf(z, 0.f) - __logf(1.0f + __expf(-fabsf(z)))) * (1.0f / 16.0f);
;         run += la; bc[r] = run; }
;     segtot[seg * 128 + d] = run;
;     __syncthreads();
;     float off = 0.f; tot = 0.f;
; #pragma unroll
;     for (int s2 = 0; s2 < 4; ++s2) { const float v = segtot[s2 * 128 + d]; tot += v; if (s2 < seg) off += v; }
;     ...
;           for (int r = 0; r < 32; ++r) { const int i = seg * 32 + r; const bf16_t* row = proj + (size_t)(t0 + i) * NMAIN + h * 128 + d;
;               const float qv = bf2f(row[C_GQ]), kv = bf2f(row[C_GK]);
;               qgs[i * GP + d] = (bf16_t)f2bf(qv * 0.08838834764831845f * __expf(bc[r])); kgs[i * GP + d] = (bf16_t)f2bf(kv * __expf(-bc[r])); } }
	v_add_f32_e32 v47, 1.0, v47
	v_mov_b32_e32 v48, v56
	v_fmamk_f32 v45, v45, 0x3d800000, v44
	v_log_f32_e32 v54, v47
	v_sub_f32_e32 v47, v55, v48
	v_fmamk_f32 v55, v47, 0x3d800000, v45
	v_min_f32_e32 v56, 0, v238
	v_mul_f32_e32 v50, 0x3f317217, v54
	v_fma_f32 v57, v54, s35, -v50
	v_fmac_f32_e32 v57, 0x3377d1cf, v54
	v_mul_f32_e64 v47, |v239|, s33
	v_exp_f32_e32 v47, v47
	v_fmac_f32_e32 v57, 0x3f317217, v54
	v_add_f32_e32 v47, 1.0, v47
	v_mov_b32_e32 v48, v57
	v_min_f32_e32 v57, 0, v239
	v_log_f32_e32 v54, v47
	v_sub_f32_e32 v47, v56, v48
	v_fmamk_f32 v56, v47, 0x3d800000, v55
	v_mul_f32_e32 v50, 0x3f317217, v54
	v_fma_f32 v58, v54, s35, -v50
	v_fmac_f32_e32 v58, 0x3377d1cf, v54
	v_mul_f32_e64 v47, |v240|, s33
	v_exp_f32_e32 v47, v47
	v_fmac_f32_e32 v58, 0x3f317217, v54
	v_add_f32_e32 v47, 1.0, v47
	v_mov_b32_e32 v48, v58
	v_min_f32_e32 v58, 0, v240
	v_log_f32_e32 v54, v47
	v_sub_f32_e32 v47, v57, v48
	v_fmamk_f32 v57, v47, 0x3d800000, v56
	v_mul_f32_e32 v50, 0x3f317217, v54
	v_fma_f32 v59, v54, s35, -v50
	v_fmac_f32_e32 v59, 0x3377d1cf, v54
	v_mul_f32_e64 v2, |v241|, s33
	v_exp_f32_e32 v2, v2
	v_fmac_f32_e32 v59, 0x3f317217, v54
	v_add_f32_e32 v2, 1.0, v2
	v_mov_b32_e32 v3, v59
	v_sub_f32_e32 v3, v58, v3
	v_log_f32_e32 v2, v2
	v_fmamk_f32 v19, v3, 0x3d800000, v57
	v_min_f32_e32 v0, 0, v241
	v_mul_f32_e32 v3, 0x3f317217, v2
	v_fma_f32 v3, v2, s35, -v3
	v_fmac_f32_e32 v3, 0x3377d1cf, v2
	v_fmac_f32_e32 v3, 0x3f317217, v2
	s_nop 1
	v_mov_b32_e32 v2, v3
	v_sub_f32_e32 v0, v0, v2
	s_and_b32 s6, s36, 0x3fffff80
	v_fmamk_f32 v0, v0, 0x3d800000, v19
	v_lshl_add_u32 v2, s6, 2, v118
	ds_write_b32 v2, v0
	s_waitcnt lgkmcnt(0)
	s_barrier
	v_add_u32_e32 v81, s44, v120
	v_mad_i64_i32 v[188:189], s[100:101], v81, s48, v[82:83]
	global_load_ushort v210, v[188:189], off
	global_load_ushort v211, v[188:189], off offset:1024
	v_add_u32_e32 v81, s44, v122
	v_mad_i64_i32 v[188:189], s[100:101], v81, s48, v[82:83]
	global_load_ushort v212, v[188:189], off
	global_load_ushort v213, v[188:189], off offset:1024
	v_add_u32_e32 v81, s44, v124
	v_mad_i64_i32 v[188:189], s[100:101], v81, s48, v[82:83]
	global_load_ushort v214, v[188:189], off
	global_load_ushort v215, v[188:189], off offset:1024
	v_add_u32_e32 v81, s44, v126
	v_mad_i64_i32 v[188:189], s[100:101], v81, s48, v[82:83]
	global_load_ushort v216, v[188:189], off
	global_load_ushort v217, v[188:189], off offset:1024
	v_add_u32_e32 v81, s44, v128
	v_mad_i64_i32 v[188:189], s[100:101], v81, s48, v[82:83]
	global_load_ushort v218, v[188:189], off
	global_load_ushort v219, v[188:189], off offset:1024
	v_add_u32_e32 v81, s44, v130
	v_mad_i64_i32 v[188:189], s[100:101], v81, s48, v[82:83]
	global_load_ushort v220, v[188:189], off
	global_load_ushort v221, v[188:189], off offset:1024
	v_add_u32_e32 v81, s44, v132
	v_mad_i64_i32 v[188:189], s[100:101], v81, s48, v[82:83]
	global_load_ushort v222, v[188:189], off
	global_load_ushort v223, v[188:189], off offset:1024
	v_add_u32_e32 v81, s44, v134
	v_mad_i64_i32 v[188:189], s[100:101], v81, s48, v[82:83]
	global_load_ushort v224, v[188:189], off
	global_load_ushort v225, v[188:189], off offset:1024
	v_add_u32_e32 v81, s44, v136
	v_mad_i64_i32 v[188:189], s[100:101], v81, s48, v[82:83]
	global_load_ushort v226, v[188:189], off
	global_load_ushort v227, v[188:189], off offset:1024
	v_add_u32_e32 v81, s44, v138
	v_mad_i64_i32 v[188:189], s[100:101], v81, s48, v[82:83]
	global_load_ushort v228, v[188:189], off
	global_load_ushort v229, v[188:189], off offset:1024
	v_add_u32_e32 v81, s44, v140
	v_mad_i64_i32 v[188:189], s[100:101], v81, s48, v[82:83]
	global_load_ushort v230, v[188:189], off
	global_load_ushort v231, v[188:189], off offset:1024
	v_add_u32_e32 v81, s44, v142
	v_mad_i64_i32 v[188:189], s[100:101], v81, s48, v[82:83]
	global_load_ushort v232, v[188:189], off
	global_load_ushort v233, v[188:189], off offset:1024
	v_add_u32_e32 v81, s44, v144
	v_mad_i64_i32 v[188:189], s[100:101], v81, s48, v[82:83]
	global_load_ushort v234, v[188:189], off
	global_load_ushort v235, v[188:189], off offset:1024
	v_add_u32_e32 v81, s44, v146
	v_mad_i64_i32 v[188:189], s[100:101], v81, s48, v[82:83]
	global_load_ushort v236, v[188:189], off
	global_load_ushort v237, v[188:189], off offset:1024
	v_add_u32_e32 v81, s44, v148
	v_mad_i64_i32 v[188:189], s[100:101], v81, s48, v[82:83]
	global_load_ushort v238, v[188:189], off
	global_load_ushort v239, v[188:189], off offset:1024
	v_add_u32_e32 v81, s44, v150
	v_mad_i64_i32 v[188:189], s[100:101], v81, s48, v[82:83]
	global_load_ushort v240, v[188:189], off
	global_load_ushort v241, v[188:189], off offset:1024
	ds_read2st64_b32 v[2:3], v118 offset1:2
	s_cmp_gt_i32 s9, 0
	ds_read2st64_b32 v[4:5], v118 offset0:4 offset1:6
	s_cselect_b64 vcc, -1, 0
	s_cmp_gt_i32 s9, 1
	s_waitcnt lgkmcnt(1)
	v_add_f32_e32 v2, 0, v2
	v_cndmask_b32_e32 v2, 0, v2, vcc
	v_add_f32_e32 v3, v3, v2
	s_cselect_b64 vcc, -1, 0
	v_cndmask_b32_e32 v2, v2, v3, vcc
	s_cmp_gt_i32 s9, 2
	s_waitcnt lgkmcnt(0)
; __device__ __forceinline__ float bf2f(bf16_t v) { return __uint_as_float((unsigned)v << 16); }
; __device__ __forceinline__ unsigned f2bf(float f) { return (unsigned)__builtin_bit_cast(unsigned short, (__bf16)f); }
; __device__ __forceinline__ void gla_bcum(KArgs a, int tid, int t0, int h, LAS float* segtot, LAS float* glrs, float (&bc)[32], float& tot) {
;     ...
;     float off = 0.f; tot = 0.f;
; #pragma unroll
;     for (int s2 = 0; s2 < 4; ++s2) { const float v = segtot[s2 * 128 + d]; tot += v; if (s2 < seg) off += v; }
; #pragma unroll
;     for (int r = 0; r < 32; ++r) bc[r] += off;
;     ...
;           for (int r = 0; r < 32; ++r) { const int i = seg * 32 + r; const bf16_t* row = proj + (size_t)(t0 + i) * NMAIN + h * 128 + d;
;               const float qv = bf2f(row[C_GQ]), kv = bf2f(row[C_GK]);
;               qgs[i * GP + d] = (bf16_t)f2bf(qv * 0.08838834764831845f * __expf(bc[r])); kgs[i * GP + d] = (bf16_t)f2bf(kv * __expf(-bc[r])); } }
	v_add_f32_e32 v3, v4, v2
	s_cselect_b64 vcc, -1, 0
	s_cmp_gt_i32 s9, 3
	v_cndmask_b32_e32 v6, v2, v3, vcc
	s_cselect_b64 vcc, -1, 0
	s_lshl_b32 s36, s1, 8
	v_lshl_add_u64 v[2:3], v[92:93], 0, s[36:37]
	v_add_f32_e32 v7, v5, v6
	v_cndmask_b32_e32 v50, v6, v7, vcc
	v_add_f32_e32 v53, v18, v50
	v_add_f32_e32 v18, v35, v50
	v_add_f32_e32 v17, v36, v50
	v_add_f32_e32 v54, v20, v50
	v_mul_f32_e32 v20, 0x3fb8aa3b, v53
	v_add_f32_e32 v15, v38, v50
	v_exp_f32_e32 v38, v20
	v_mul_f32_e32 v20, 0xbfb8aa3b, v53
	v_add_f32_e32 v14, v39, v50
	v_exp_f32_e32 v39, v20
	v_add_f32_e32 v58, v21, v50
	v_add_f32_e32 v13, v40, v50
	v_add_f32_e32 v12, v41, v50
	v_add_f32_e32 v4, v19, v50
	v_add_f32_e32 v16, v37, v50
	v_mul_f32_e32 v20, 0x3fb8aa3b, v54
	v_add_f32_e32 v11, v42, v50
	v_add_f32_e32 v10, v43, v50
	v_add_f32_e32 v9, v44, v50
	v_add_f32_e32 v8, v45, v50
	v_add_f32_e32 v22, v22, v50
	v_add_f32_e32 v23, v23, v50
	v_add_f32_e32 v24, v24, v50
	v_add_f32_e32 v25, v25, v50
	v_add_f32_e32 v26, v26, v50
	v_add_f32_e32 v27, v27, v50
	v_add_f32_e32 v28, v28, v50
	v_add_f32_e32 v29, v29, v50
	v_add_f32_e32 v30, v30, v50
	v_add_f32_e32 v31, v31, v50
	v_add_f32_e32 v32, v32, v50
	v_add_f32_e32 v33, v33, v50
	v_add_f32_e32 v34, v34, v50
	s_mov_b32 s9, s37
	v_add_f32_e32 v7, v55, v50
	v_add_f32_e32 v6, v56, v50
	v_add_f32_e32 v5, v57, v50
	v_add_f32_e32 v0, v50, v0
	s_andn2_b64 vcc, exec, s[38:39]
	s_waitcnt vmcnt(31)
	v_lshlrev_b32_e32 v19, 16, v210
	v_mul_f32_e32 v19, 0x3db504f3, v19
	v_mul_f32_e32 v19, v19, v38
	s_waitcnt vmcnt(30)
	v_lshlrev_b32_e32 v37, 16, v211
	v_cvt_pk_bf16_f32 v19, v19, s0
	ds_write_b16 v121, v19
	v_mul_f32_e32 v19, v39, v37
	v_exp_f32_e32 v38, v20
	v_mul_f32_e32 v20, 0xbfb8aa3b, v54
	v_cvt_pk_bf16_f32 v19, v19, s0
	v_exp_f32_e32 v39, v20
	ds_write_b16 v121, v19 offset:34816
	s_waitcnt vmcnt(29)
	v_lshlrev_b32_e32 v19, 16, v212
	v_mul_f32_e32 v19, 0x3db504f3, v19
	v_mul_f32_e32 v19, v38, v19
	s_waitcnt vmcnt(28)
	v_lshlrev_b32_e32 v37, 16, v213
	v_cvt_pk_bf16_f32 v19, v19, s0
	v_mul_f32_e32 v20, 0x3fb8aa3b, v58
	ds_write_b16 v123, v19
	v_mul_f32_e32 v19, v39, v37
	v_exp_f32_e32 v38, v20
	v_mul_f32_e32 v20, 0xbfb8aa3b, v58
	v_cvt_pk_bf16_f32 v19, v19, s0
	v_exp_f32_e32 v39, v20
	ds_write_b16 v123, v19 offset:34816
	s_waitcnt vmcnt(27)
	v_lshlrev_b32_e32 v19, 16, v214
	v_mul_f32_e32 v19, 0x3db504f3, v19
	v_mul_f32_e32 v19, v38, v19
	s_waitcnt vmcnt(26)
	v_lshlrev_b32_e32 v37, 16, v215
	v_cvt_pk_bf16_f32 v19, v19, s0
	v_mul_f32_e32 v20, 0x3fb8aa3b, v22
	ds_write_b16 v125, v19
	v_mul_f32_e32 v19, v39, v37
	v_exp_f32_e32 v38, v20
	v_mul_f32_e32 v20, 0xbfb8aa3b, v22
	v_cvt_pk_bf16_f32 v19, v19, s0
	v_exp_f32_e32 v22, v20
	ds_write_b16 v125, v19 offset:34816
	s_waitcnt vmcnt(25)
	v_lshlrev_b32_e32 v19, 16, v216
	v_mul_f32_e32 v19, 0x3db504f3, v19
	v_mul_f32_e32 v19, v38, v19
	s_waitcnt vmcnt(24)
	v_lshlrev_b32_e32 v37, 16, v217
	v_cvt_pk_bf16_f32 v19, v19, s0
	ds_write_b16 v127, v19
	v_mul_f32_e32 v19, v22, v37
	v_cvt_pk_bf16_f32 v19, v19, s0
	v_mul_f32_e32 v20, 0x3fb8aa3b, v23
	ds_write_b16 v127, v19 offset:34816
	s_waitcnt vmcnt(23)
	v_lshlrev_b32_e32 v19, 16, v218
	v_exp_f32_e32 v35, v20
	v_mul_f32_e32 v20, 0xbfb8aa3b, v23
	v_exp_f32_e32 v23, v20
	s_waitcnt vmcnt(22)
	v_lshlrev_b32_e32 v22, 16, v219
	v_mul_f32_e32 v19, 0x3db504f3, v19
	v_mul_f32_e32 v19, v35, v19
	v_cvt_pk_bf16_f32 v19, v19, s0
	v_mul_f32_e32 v20, 0x3fb8aa3b, v24
	ds_write_b16 v129, v19
	v_mul_f32_e32 v19, v23, v22
	v_exp_f32_e32 v23, v20
	v_mul_f32_e32 v20, 0xbfb8aa3b, v24
	v_cvt_pk_bf16_f32 v19, v19, s0
	v_exp_f32_e32 v24, v20
	ds_write_b16 v129, v19 offset:34816
	s_waitcnt vmcnt(21)
	v_lshlrev_b32_e32 v19, 16, v220
	v_mul_f32_e32 v19, 0x3db504f3, v19
	v_mul_f32_e32 v19, v23, v19
	s_waitcnt vmcnt(20)
	v_lshlrev_b32_e32 v22, 16, v221
	v_cvt_pk_bf16_f32 v19, v19, s0
	v_mul_f32_e32 v20, 0x3fb8aa3b, v25
	ds_write_b16 v131, v19
	v_mul_f32_e32 v19, v24, v22
	v_exp_f32_e32 v23, v20
	v_mul_f32_e32 v20, 0xbfb8aa3b, v25
	v_cvt_pk_bf16_f32 v19, v19, s0
	v_exp_f32_e32 v24, v20
	ds_write_b16 v131, v19 offset:34816
	s_waitcnt vmcnt(19)
	v_lshlrev_b32_e32 v19, 16, v222
	v_mul_f32_e32 v19, 0x3db504f3, v19
	v_mul_f32_e32 v19, v23, v19
	s_waitcnt vmcnt(18)
	v_lshlrev_b32_e32 v22, 16, v223
	v_cvt_pk_bf16_f32 v19, v19, s0
	v_mul_f32_e32 v20, 0x3fb8aa3b, v26
	ds_write_b16 v133, v19
	v_mul_f32_e32 v19, v24, v22
	v_exp_f32_e32 v23, v20
	v_mul_f32_e32 v20, 0xbfb8aa3b, v26
	v_cvt_pk_bf16_f32 v19, v19, s0
	v_exp_f32_e32 v24, v20
	ds_write_b16 v133, v19 offset:34816
	s_waitcnt vmcnt(17)
	v_lshlrev_b32_e32 v19, 16, v224
	v_mul_f32_e32 v19, 0x3db504f3, v19
	v_mul_f32_e32 v19, v23, v19
	s_waitcnt vmcnt(16)
	v_lshlrev_b32_e32 v22, 16, v225
	v_cvt_pk_bf16_f32 v19, v19, s0
	v_mul_f32_e32 v20, 0x3fb8aa3b, v27
	ds_write_b16 v135, v19
	v_mul_f32_e32 v19, v24, v22
	v_exp_f32_e32 v23, v20
	v_mul_f32_e32 v20, 0xbfb8aa3b, v27
	v_cvt_pk_bf16_f32 v19, v19, s0
	v_exp_f32_e32 v24, v20
	ds_write_b16 v135, v19 offset:34816
	s_waitcnt vmcnt(15)
	v_lshlrev_b32_e32 v19, 16, v226
	v_mul_f32_e32 v19, 0x3db504f3, v19
	v_mul_f32_e32 v19, v23, v19
	s_waitcnt vmcnt(14)
	v_lshlrev_b32_e32 v22, 16, v227
	v_cvt_pk_bf16_f32 v19, v19, s0
	v_mul_f32_e32 v20, 0x3fb8aa3b, v28
	ds_write_b16 v137, v19
	v_mul_f32_e32 v19, v24, v22
	v_exp_f32_e32 v23, v20
	v_mul_f32_e32 v20, 0xbfb8aa3b, v28
	v_cvt_pk_bf16_f32 v19, v19, s0
	v_exp_f32_e32 v24, v20
	ds_write_b16 v137, v19 offset:34816
	s_waitcnt vmcnt(13)
	v_lshlrev_b32_e32 v19, 16, v228
	v_mul_f32_e32 v19, 0x3db504f3, v19
	v_mul_f32_e32 v19, v23, v19
	s_waitcnt vmcnt(12)
; __device__ __forceinline__ float bf2f(bf16_t v) { return __uint_as_float((unsigned)v << 16); }
; __device__ __forceinline__ unsigned f2bf(float f) { return (unsigned)__builtin_bit_cast(unsigned short, (__bf16)f); }
;     ...
;           for (int r = 0; r < 32; ++r) { const int i = seg * 32 + r; const bf16_t* row = proj + (size_t)(t0 + i) * NMAIN + h * 128 + d;
;               const float qv = bf2f(row[C_GQ]), kv = bf2f(row[C_GK]);
;               qgs[i * GP + d] = (bf16_t)f2bf(qv * 0.08838834764831845f * __expf(bc[r])); kgs[i * GP + d] = (bf16_t)f2bf(kv * __expf(-bc[r])); } }
	v_lshlrev_b32_e32 v22, 16, v229
	v_cvt_pk_bf16_f32 v19, v19, s0
	v_mul_f32_e32 v20, 0x3fb8aa3b, v29
	ds_write_b16 v139, v19
	v_mul_f32_e32 v19, v24, v22
	v_exp_f32_e32 v23, v20
	v_mul_f32_e32 v20, 0xbfb8aa3b, v29
	v_cvt_pk_bf16_f32 v19, v19, s0
	v_exp_f32_e32 v24, v20
	ds_write_b16 v139, v19 offset:34816
	s_waitcnt vmcnt(11)
	v_lshlrev_b32_e32 v19, 16, v230
	v_mul_f32_e32 v19, 0x3db504f3, v19
	v_mul_f32_e32 v19, v23, v19
	s_waitcnt vmcnt(10)
	v_lshlrev_b32_e32 v22, 16, v231
	v_cvt_pk_bf16_f32 v19, v19, s0
	v_mul_f32_e32 v20, 0x3fb8aa3b, v30
	ds_write_b16 v141, v19
	v_mul_f32_e32 v19, v24, v22
	v_exp_f32_e32 v23, v20
	v_mul_f32_e32 v20, 0xbfb8aa3b, v30
	v_cvt_pk_bf16_f32 v19, v19, s0
	v_exp_f32_e32 v24, v20
	v_add_u32_e32 v20, s44, v152
	ds_write_b16 v141, v19 offset:34816
	v_mad_i64_i32 v[20:21], s[6:7], v20, s48, v[2:3]
	s_waitcnt vmcnt(9)
	v_lshlrev_b32_e32 v19, 16, v232
	global_load_ushort v25, v[20:21], off
	global_load_ushort v30, v[20:21], off offset:1024
	v_mul_f32_e32 v19, 0x3db504f3, v19
	v_mul_f32_e32 v19, v23, v19
	s_waitcnt vmcnt(10)
	v_lshlrev_b32_e32 v22, 16, v233
	v_cvt_pk_bf16_f32 v19, v19, s0
	v_mul_f32_e32 v20, 0x3fb8aa3b, v31
	ds_write_b16 v143, v19
	v_mul_f32_e32 v19, v24, v22
	v_exp_f32_e32 v23, v20
	v_mul_f32_e32 v20, 0xbfb8aa3b, v31
	v_cvt_pk_bf16_f32 v19, v19, s0
	v_exp_f32_e32 v24, v20
	v_add_u32_e32 v20, s44, v154
	ds_write_b16 v143, v19 offset:34816
	v_mad_i64_i32 v[20:21], s[6:7], v20, s48, v[2:3]
	s_waitcnt vmcnt(9)
	v_lshlrev_b32_e32 v19, 16, v234
	global_load_ushort v26, v[20:21], off
	global_load_ushort v31, v[20:21], off offset:1024
	v_mul_f32_e32 v19, 0x3db504f3, v19
	v_mul_f32_e32 v19, v23, v19
	s_waitcnt vmcnt(10)
	v_lshlrev_b32_e32 v22, 16, v235
	v_cvt_pk_bf16_f32 v19, v19, s0
	v_mul_f32_e32 v20, 0x3fb8aa3b, v32
	ds_write_b16 v145, v19
	v_mul_f32_e32 v19, v24, v22
	v_exp_f32_e32 v23, v20
	v_mul_f32_e32 v20, 0xbfb8aa3b, v32
	v_cvt_pk_bf16_f32 v19, v19, s0
	v_exp_f32_e32 v24, v20
	v_add_u32_e32 v20, s44, v156
	ds_write_b16 v145, v19 offset:34816
	v_mad_i64_i32 v[20:21], s[6:7], v20, s48, v[2:3]
	s_waitcnt vmcnt(9)
	v_lshlrev_b32_e32 v19, 16, v236
	global_load_ushort v27, v[20:21], off
	global_load_ushort v32, v[20:21], off offset:1024
	v_mul_f32_e32 v19, 0x3db504f3, v19
	v_mul_f32_e32 v19, v23, v19
	s_waitcnt vmcnt(10)
	v_lshlrev_b32_e32 v22, 16, v237
	v_cvt_pk_bf16_f32 v19, v19, s0
	v_mul_f32_e32 v20, 0x3fb8aa3b, v33
	ds_write_b16 v147, v19
	v_mul_f32_e32 v19, v24, v22
	v_exp_f32_e32 v23, v20
	v_cvt_pk_bf16_f32 v19, v19, s0
	v_mul_f32_e32 v20, 0xbfb8aa3b, v33
	ds_write_b16 v147, v19 offset:34816
	s_waitcnt vmcnt(9)
	v_lshlrev_b32_e32 v19, 16, v238
	v_exp_f32_e32 v24, v20
	v_mul_f32_e32 v19, 0x3db504f3, v19
	v_add_u32_e32 v20, s44, v158
	v_mad_i64_i32 v[20:21], s[6:7], v20, s48, v[2:3]
	v_mul_f32_e32 v19, v23, v19
	s_waitcnt vmcnt(8)
	v_lshlrev_b32_e32 v22, 16, v239
	global_load_ushort v28, v[20:21], off
	global_load_ushort v33, v[20:21], off offset:1024
	v_cvt_pk_bf16_f32 v19, v19, s0
	v_mul_f32_e32 v20, 0x3fb8aa3b, v34
	ds_write_b16 v149, v19
	v_mul_f32_e32 v19, v24, v22
	v_exp_f32_e32 v23, v20
	v_mul_f32_e32 v20, 0xbfb8aa3b, v34
	v_cvt_pk_bf16_f32 v19, v19, s0
	v_exp_f32_e32 v24, v20
	v_add_u32_e32 v20, s44, v160
	ds_write_b16 v149, v19 offset:34816
	v_mad_i64_i32 v[20:21], s[6:7], v20, s48, v[2:3]
	s_waitcnt vmcnt(9)
	v_lshlrev_b32_e32 v19, 16, v240
	global_load_ushort v29, v[20:21], off
	s_nop 0
	global_load_ushort v20, v[20:21], off offset:1024
	v_mul_f32_e32 v19, 0x3db504f3, v19
	v_mul_f32_e32 v19, v23, v19
	s_waitcnt vmcnt(10)
	v_lshlrev_b32_e32 v22, 16, v241
	v_cvt_pk_bf16_f32 v19, v19, s0
	ds_write_b16 v151, v19
	v_mul_f32_e32 v19, v24, v22
	v_cvt_pk_bf16_f32 v19, v19, s0
	ds_write_b16 v151, v19 offset:34816
	s_waitcnt vmcnt(9)
	v_lshlrev_b32_e32 v19, 16, v25
	v_mul_f32_e32 v22, 0x3db504f3, v19
	v_mul_f32_e32 v19, 0x3fb8aa3b, v18
	v_mul_f32_e32 v18, 0xbfb8aa3b, v18
	v_exp_f32_e32 v24, v18
	v_add_u32_e32 v18, s44, v162
	v_exp_f32_e32 v23, v19
	v_mad_i64_i32 v[18:19], s[6:7], v18, s48, v[2:3]
	s_waitcnt vmcnt(8)
	v_lshlrev_b32_e32 v21, 16, v30
	global_load_ushort v25, v[18:19], off
	global_load_ushort v30, v[18:19], off offset:1024
	v_mul_f32_e32 v18, v23, v22
	v_cvt_pk_bf16_f32 v18, v18, s0
	ds_write_b16 v153, v18
	v_mul_f32_e32 v18, v24, v21
	v_cvt_pk_bf16_f32 v18, v18, s0
	ds_write_b16 v153, v18 offset:34816
	s_waitcnt vmcnt(9)
	v_lshlrev_b32_e32 v18, 16, v26
	v_mul_f32_e32 v22, 0x3db504f3, v18
	v_mul_f32_e32 v18, 0x3fb8aa3b, v17
	v_exp_f32_e32 v23, v18
	v_mul_f32_e32 v17, 0xbfb8aa3b, v17
	v_exp_f32_e32 v17, v17
	v_add_u32_e32 v18, s44, v164
	v_mad_i64_i32 v[18:19], s[6:7], v18, s48, v[2:3]
	s_waitcnt vmcnt(8)
	v_lshlrev_b32_e32 v21, 16, v31
	global_load_ushort v24, v[18:19], off
	global_load_ushort v26, v[18:19], off offset:1024
	v_mul_f32_e32 v18, v23, v22
	v_cvt_pk_bf16_f32 v18, v18, s0
	v_mul_f32_e32 v17, v17, v21
	ds_write_b16 v155, v18
	v_cvt_pk_bf16_f32 v17, v17, s0
	v_add_u32_e32 v18, s44, v166
	ds_write_b16 v155, v17 offset:34816
	v_mad_i64_i32 v[18:19], s[6:7], v18, s48, v[2:3]
	global_load_ushort v22, v[18:19], off
	s_nop 0
	global_load_ushort v18, v[18:19], off offset:1024
	v_mul_f32_e32 v19, 0x3fb8aa3b, v16
	v_mul_f32_e32 v16, 0xbfb8aa3b, v16
	v_exp_f32_e32 v16, v16
	v_exp_f32_e32 v19, v19
	s_waitcnt vmcnt(11)
	v_lshlrev_b32_e32 v17, 16, v27
	s_waitcnt vmcnt(10)
	v_lshlrev_b32_e32 v21, 16, v32
	v_mul_f32_e32 v17, 0x3db504f3, v17
	v_mul_f32_e32 v16, v16, v21
	v_mul_f32_e32 v17, v19, v17
	v_cvt_pk_bf16_f32 v16, v16, s0
	v_cvt_pk_bf16_f32 v17, v17, s0
	ds_write_b16 v157, v16 offset:34816
	v_add_u32_e32 v16, s44, v168
	ds_write_b16 v157, v17
	v_mad_i64_i32 v[16:17], s[6:7], v16, s48, v[2:3]
	global_load_ushort v23, v[16:17], off
	s_nop 0
	global_load_ushort v16, v[16:17], off offset:1024
	v_mul_f32_e32 v17, 0x3fb8aa3b, v15
	v_mul_f32_e32 v15, 0xbfb8aa3b, v15
	v_exp_f32_e32 v15, v15
	s_waitcnt vmcnt(10)
; #define LAS __attribute__((address_space(3)))
; __device__ __forceinline__ float bf2f(bf16_t v) { return __uint_as_float((unsigned)v << 16); }
; __device__ __forceinline__ unsigned f2bf(float f) { return (unsigned)__builtin_bit_cast(unsigned short, (__bf16)f); }
; __device__ __forceinline__ void gla_stage_vT(const bf16_t* proj, int tid, int t0, int h, LAS bf16_t* vT) {
; #pragma unroll
;     for (int q = 0; q < 8; ++q) { const int i = tid >> 2, c = (tid & 3) + 4 * q;
;         const u32x4 wv = *(const u32x4*)(proj + (size_t)(t0 + i) * NMAIN + C_GV + h * 256 + 8 * c);
;         LAS bf16_t* vp = vT + (8 * c) * GP + i;
;         vp[0 * GP] = (bf16_t)(wv.x & 0xffff); vp[1 * GP] = (bf16_t)(wv.x >> 16); vp[2 * GP] = (bf16_t)(wv.y & 0xffff); vp[3 * GP] = (bf16_t)(wv.y >> 16);
;         vp[4 * GP] = (bf16_t)(wv.z & 0xffff); vp[5 * GP] = (bf16_t)(wv.z >> 16); vp[6 * GP] = (bf16_t)(wv.w & 0xffff); vp[7 * GP] = (bf16_t)(wv.w >> 16); }
;     ...
;           for (int r = 0; r < 32; ++r) { const int i = seg * 32 + r; const bf16_t* row = proj + (size_t)(t0 + i) * NMAIN + h * 128 + d;
;               const float qv = bf2f(row[C_GQ]), kv = bf2f(row[C_GK]);
;               qgs[i * GP + d] = (bf16_t)f2bf(qv * 0.08838834764831845f * __expf(bc[r])); kgs[i * GP + d] = (bf16_t)f2bf(kv * __expf(-bc[r])); } }
	v_lshlrev_b32_e32 v21, 16, v33
	v_exp_f32_e32 v17, v17
	v_lshlrev_b32_e32 v19, 16, v28
	v_mul_f32_e32 v15, v15, v21
	v_cvt_pk_bf16_f32 v15, v15, s0
	v_mul_f32_e32 v19, 0x3db504f3, v19
	ds_write_b16 v159, v15 offset:34816
	v_mul_f32_e32 v17, v17, v19
	v_cvt_pk_bf16_f32 v17, v17, s0
	ds_write_b16 v159, v17
	s_waitcnt vmcnt(9)
	v_lshlrev_b32_e32 v15, 16, v29
	v_mul_f32_e32 v19, 0x3db504f3, v15
	v_mul_f32_e32 v15, 0x3fb8aa3b, v14
	v_mul_f32_e32 v14, 0xbfb8aa3b, v14
	v_exp_f32_e32 v21, v14
	v_add_u32_e32 v14, s44, v170
	s_waitcnt vmcnt(8)
	v_lshlrev_b32_e32 v17, 16, v20
	v_exp_f32_e32 v20, v15
	v_mad_i64_i32 v[14:15], s[6:7], v14, s48, v[2:3]
	global_load_ushort v27, v[14:15], off
	global_load_ushort v28, v[14:15], off offset:1024
	v_mul_f32_e32 v14, v20, v19
	v_cvt_pk_bf16_f32 v14, v14, s0
	ds_write_b16 v161, v14
	v_mul_f32_e32 v14, v21, v17
	v_cvt_pk_bf16_f32 v14, v14, s0
	ds_write_b16 v161, v14 offset:34816
	s_waitcnt vmcnt(9)
	v_lshlrev_b32_e32 v14, 16, v25
	v_mul_f32_e32 v19, 0x3db504f3, v14
	v_mul_f32_e32 v14, 0x3fb8aa3b, v13
	v_exp_f32_e32 v20, v14
	v_add_u32_e32 v14, s44, v172
	v_mad_i64_i32 v[14:15], s[6:7], v14, s48, v[2:3]
	global_load_ushort v21, v[14:15], off
	s_nop 0
	global_load_ushort v14, v[14:15], off offset:1024
	v_mul_f32_e32 v13, 0xbfb8aa3b, v13
	v_exp_f32_e32 v13, v13
	s_waitcnt vmcnt(10)
	v_lshlrev_b32_e32 v17, 16, v30
	v_mul_f32_e32 v15, v20, v19
	v_cvt_pk_bf16_f32 v15, v15, s0
	v_mul_f32_e32 v13, v13, v17
	v_mul_f32_e32 v17, 0x3fb8aa3b, v12
	v_mul_f32_e32 v12, 0xbfb8aa3b, v12
	v_exp_f32_e32 v12, v12
	v_exp_f32_e32 v17, v17
	ds_write_b16 v163, v15
	v_cvt_pk_bf16_f32 v13, v13, s0
	s_waitcnt vmcnt(8)
	v_lshlrev_b32_e32 v15, 16, v26
	ds_write_b16 v163, v13 offset:34816
	v_lshlrev_b32_e32 v13, 16, v24
	v_mul_f32_e32 v12, v12, v15
	v_mul_f32_e32 v13, 0x3db504f3, v13
	v_cvt_pk_bf16_f32 v12, v12, s0
	v_mul_f32_e32 v13, v17, v13
	ds_write_b16 v165, v12 offset:34816
	v_mul_f32_e32 v12, 0x3fb8aa3b, v11
	v_cvt_pk_bf16_f32 v13, v13, s0
	s_waitcnt vmcnt(6)
	v_lshlrev_b32_e32 v17, 16, v18
	v_exp_f32_e32 v18, v12
	v_add_u32_e32 v12, s44, v174
	ds_write_b16 v165, v13
	v_mad_i64_i32 v[12:13], s[6:7], v12, s48, v[2:3]
	global_load_ushort v19, v[12:13], off
	global_load_ushort v20, v[12:13], off offset:1024
	v_mul_f32_e32 v11, 0xbfb8aa3b, v11
	v_exp_f32_e32 v11, v11
	v_lshlrev_b32_e32 v15, 16, v22
	v_mul_f32_e32 v12, 0x3db504f3, v15
	v_mul_f32_e32 v12, v18, v12
	v_cvt_pk_bf16_f32 v12, v12, s0
	v_mul_f32_e32 v11, v11, v17
	ds_write_b16 v167, v12
	v_cvt_pk_bf16_f32 v11, v11, s0
	v_add_u32_e32 v12, s44, v176
	ds_write_b16 v167, v11 offset:34816
	v_mad_i64_i32 v[12:13], s[6:7], v12, s48, v[2:3]
	global_load_ushort v24, v[12:13], off
	global_load_ushort v25, v[12:13], off offset:1024
	s_waitcnt vmcnt(8)
	v_lshlrev_b32_e32 v15, 16, v16
	v_mul_f32_e32 v16, 0x3fb8aa3b, v10
	v_mul_f32_e32 v10, 0xbfb8aa3b, v10
	v_exp_f32_e32 v10, v10
	v_exp_f32_e32 v12, v16
	v_lshlrev_b32_e32 v11, 16, v23
	v_mul_f32_e32 v11, 0x3db504f3, v11
	v_mul_f32_e32 v10, v10, v15
	v_mul_f32_e32 v11, v12, v11
	v_cvt_pk_bf16_f32 v10, v10, s0
	v_cvt_pk_bf16_f32 v11, v11, s0
	ds_write_b16 v169, v10 offset:34816
	v_add_u32_e32 v10, s44, v178
	ds_write_b16 v169, v11
	v_mad_i64_i32 v[10:11], s[6:7], v10, s48, v[2:3]
	global_load_ushort v32, v[10:11], off
	global_load_ushort v33, v[10:11], off offset:1024
	s_waitcnt vmcnt(9)
	v_lshlrev_b32_e32 v10, 16, v27
	v_mul_f32_e32 v13, 0x3db504f3, v10
	v_mul_f32_e32 v10, 0x3fb8aa3b, v9
	v_exp_f32_e32 v15, v10
	v_add_u32_e32 v10, s44, v180
	v_mad_i64_i32 v[10:11], s[6:7], v10, s48, v[2:3]
	global_load_ushort v36, v[10:11], off
	global_load_ushort v37, v[10:11], off offset:1024
	v_mul_f32_e32 v9, 0xbfb8aa3b, v9
	v_exp_f32_e32 v9, v9
	s_waitcnt vmcnt(10)
	v_lshlrev_b32_e32 v12, 16, v28
	v_mul_f32_e32 v10, v15, v13
	v_cvt_pk_bf16_f32 v10, v10, s0
	v_mul_f32_e32 v9, v9, v12
	v_cvt_pk_bf16_f32 v9, v9, s0
	ds_write_b16 v171, v9 offset:34816
	ds_write_b16 v171, v10
	v_mul_f32_e32 v15, 0xbfb8aa3b, v8
	s_waitcnt vmcnt(9)
	v_lshlrev_b32_e32 v9, 16, v21
	v_mul_f32_e32 v13, 0x3db504f3, v9
	v_add_u32_e32 v9, s44, v182
	v_mad_i64_i32 v[2:3], s[6:7], v9, s48, v[2:3]
	global_load_ushort v40, v[2:3], off
	global_load_ushort v41, v[2:3], off offset:1024
	v_mul_f32_e32 v2, 0x3fb8aa3b, v8
	s_waitcnt vmcnt(10)
	v_lshlrev_b32_e32 v12, 16, v14
	v_exp_f32_e32 v14, v2
	v_add_u32_e32 v8, s44, v119
	v_mov_b64_e32 v[2:3], s[22:23]
	v_mad_i64_i32 v[2:3], s[6:7], v8, s48, v[2:3]
	v_lshl_add_u64 v[2:3], v[2:3], 0, s[8:9]
	v_lshl_add_u64 v[2:3], v[2:3], 0, v[110:111]
	global_load_dwordx4 v[8:11], v[2:3], off offset:2048
	v_exp_f32_e32 v15, v15
	v_mul_f32_e32 v13, v14, v13
	v_cvt_pk_bf16_f32 v13, v13, s0
	ds_write_b16 v173, v13
	v_mul_f32_e32 v12, v15, v12
	v_cvt_pk_bf16_f32 v12, v12, s0
	ds_write_b16 v173, v12 offset:34816
	global_load_dwordx4 v[12:15], v[2:3], off offset:2112
	s_waitcnt vmcnt(11)
	v_lshlrev_b32_e32 v16, 16, v19
	v_mul_f32_e32 v21, 0x3db504f3, v16
	v_mul_f32_e32 v16, 0x3fb8aa3b, v7
	v_exp_f32_e32 v22, v16
	global_load_dwordx4 v[16:19], v[2:3], off offset:2176
	v_mul_f32_e32 v7, 0xbfb8aa3b, v7
	v_exp_f32_e32 v7, v7
	v_mul_f32_e32 v21, v22, v21
	s_waitcnt vmcnt(11)
	v_lshlrev_b32_e32 v20, 16, v20
	v_cvt_pk_bf16_f32 v21, v21, s0
	ds_write_b16 v175, v21
	v_mul_f32_e32 v7, v7, v20
	global_load_dwordx4 v[20:23], v[2:3], off offset:2240
	v_cvt_pk_bf16_f32 v7, v7, s0
	ds_write_b16 v175, v7 offset:34816
	v_mul_f32_e32 v7, 0x3fb8aa3b, v6
	v_exp_f32_e32 v7, v7
	s_waitcnt vmcnt(11)
	v_lshlrev_b32_e32 v24, 16, v24
	v_mul_f32_e32 v24, 0x3db504f3, v24
	s_waitcnt vmcnt(10)
; #define LAS __attribute__((address_space(3)))
; #define X make_ctx(lds_raw)
; __device__ __forceinline__ void gla_stage_vT(const bf16_t* proj, int tid, int t0, int h, LAS bf16_t* vT) {
;     ...
;     for (int q = 0; q < 8; ++q) { const int i = tid >> 2, c = (tid & 3) + 4 * q;
;         const u32x4 wv = *(const u32x4*)(proj + (size_t)(t0 + i) * NMAIN + C_GV + h * 256 + 8 * c);
;         LAS bf16_t* vp = vT + (8 * c) * GP + i;
;         vp[0 * GP] = (bf16_t)(wv.x & 0xffff); vp[1 * GP] = (bf16_t)(wv.x >> 16); vp[2 * GP] = (bf16_t)(wv.y & 0xffff); vp[3 * GP] = (bf16_t)(wv.y >> 16);
;         vp[4 * GP] = (bf16_t)(wv.z & 0xffff); vp[5 * GP] = (bf16_t)(wv.z >> 16); vp[6 * GP] = (bf16_t)(wv.w & 0xffff); vp[7 * GP] = (bf16_t)(wv.w >> 16); }
;     ...
;         bf16x8 afr[4];
; #pragma unroll
;         for (int ks = 0; ks < 4; ++ks) afr[ks] = *(const LAS bf16x8*)(qgs + (i0 + fr) * GP + 32 * ks + 8 * fq);
;     ...
;         if (n > 0) {
;             __syncthreads();
;             const bf16_t* sb = (const bf16_t*)kvt + (size_t)unit * 32768;
; #pragma unroll
;             for (int q = 0; q < 8; ++q) { const int sidx = X.tid + 512 * q; const u32x4 wv = *(const u32x4*)(sb + (size_t)sidx * 8);
;                 *(LAS u32x4*)(vT + (sidx >> 4) * GP + (sidx & 15) * 8) = wv; }
	v_lshlrev_b32_e32 v28, 16, v25
	v_mul_f32_e32 v7, v7, v24
	global_load_dwordx4 v[24:27], v[2:3], off offset:2304
	v_mul_f32_e32 v6, 0xbfb8aa3b, v6
	v_exp_f32_e32 v6, v6
	v_cvt_pk_bf16_f32 v7, v7, s0
	ds_write_b16 v177, v7
	v_mul_f32_e32 v6, v6, v28
	global_load_dwordx4 v[28:31], v[2:3], off offset:2368
	v_cvt_pk_bf16_f32 v6, v6, s0
	ds_write_b16 v177, v6 offset:34816
	s_waitcnt vmcnt(11)
	v_lshlrev_b32_e32 v7, 16, v32
	s_waitcnt vmcnt(10)
	v_lshlrev_b32_e32 v38, 16, v33
	global_load_dwordx4 v[32:35], v[2:3], off offset:2432
	v_mul_f32_e32 v6, 0x3fb8aa3b, v5
	v_mul_f32_e32 v5, 0xbfb8aa3b, v5
	v_exp_f32_e32 v6, v6
	v_exp_f32_e32 v5, v5
	v_mul_f32_e32 v7, 0x3db504f3, v7
	v_mul_f32_e32 v6, v6, v7
	v_mul_f32_e32 v5, v5, v38
	v_cvt_pk_bf16_f32 v6, v6, s0
	v_cvt_pk_bf16_f32 v5, v5, s0
	ds_write_b16 v179, v6
	ds_write_b16 v179, v5 offset:34816
	s_waitcnt vmcnt(10)
	v_lshlrev_b32_e32 v5, 16, v36
	s_waitcnt vmcnt(9)
	v_lshlrev_b32_e32 v6, 16, v37
	global_load_dwordx4 v[36:39], v[2:3], off offset:2496
	v_mul_f32_e32 v7, 0x3fb8aa3b, v4
	v_exp_f32_e32 v2, v7
	v_mul_f32_e32 v4, 0xbfb8aa3b, v4
	v_exp_f32_e32 v4, v4
	v_mul_f32_e32 v3, 0x3db504f3, v5
	v_mul_f32_e32 v2, v2, v3
	v_cvt_pk_bf16_f32 v2, v2, s0
	ds_write_b16 v181, v2
	v_mul_f32_e32 v2, v4, v6
	v_mul_f32_e32 v4, 0x3fb8aa3b, v0
	v_mul_f32_e32 v0, 0xbfb8aa3b, v0
	v_exp_f32_e32 v4, v4
	v_exp_f32_e32 v0, v0
	v_cvt_pk_bf16_f32 v2, v2, s0
	ds_write_b16 v181, v2 offset:34816
	s_waitcnt vmcnt(9)
	v_lshlrev_b32_e32 v2, 16, v40
	s_waitcnt vmcnt(8)
	v_lshlrev_b32_e32 v3, 16, v41
	v_mul_f32_e32 v2, 0x3db504f3, v2
	v_mul_f32_e32 v2, v4, v2
	v_mul_f32_e32 v0, v0, v3
	v_cvt_pk_bf16_f32 v2, v2, s0
	v_cvt_pk_bf16_f32 v0, v0, s0
	ds_write_b16 v183, v2
	ds_write_b16 v183, v0 offset:34816
	s_waitcnt vmcnt(7)
	ds_write_b16 v203, v8
	ds_write_b16_d16_hi v203, v8 offset:272
	ds_write_b16 v203, v9 offset:544
	ds_write_b16_d16_hi v203, v9 offset:816
	ds_write_b16 v203, v10 offset:1088
	ds_write_b16_d16_hi v203, v10 offset:1360
	ds_write_b16 v203, v11 offset:1632
	ds_write_b16_d16_hi v203, v11 offset:1904
	s_waitcnt vmcnt(6)
	ds_write_b16 v203, v12 offset:8704
	ds_write_b16_d16_hi v203, v12 offset:8976
	ds_write_b16 v203, v13 offset:9248
	ds_write_b16_d16_hi v203, v13 offset:9520
	ds_write_b16 v203, v14 offset:9792
	ds_write_b16_d16_hi v203, v14 offset:10064
	ds_write_b16 v203, v15 offset:10336
	ds_write_b16_d16_hi v203, v15 offset:10608
	s_waitcnt vmcnt(5)
	ds_write_b16 v203, v16 offset:17408
	ds_write_b16_d16_hi v203, v16 offset:17680
	ds_write_b16 v203, v17 offset:17952
	ds_write_b16_d16_hi v203, v17 offset:18224
	ds_write_b16 v203, v18 offset:18496
	ds_write_b16_d16_hi v203, v18 offset:18768
	ds_write_b16 v203, v19 offset:19040
	ds_write_b16_d16_hi v203, v19 offset:19312
	s_waitcnt vmcnt(4)
	ds_write_b16 v203, v20 offset:26112
	ds_write_b16_d16_hi v203, v20 offset:26384
	ds_write_b16 v203, v21 offset:26656
	ds_write_b16_d16_hi v203, v21 offset:26928
	ds_write_b16 v203, v22 offset:27200
	ds_write_b16_d16_hi v203, v22 offset:27472
	ds_write_b16 v203, v23 offset:27744
	ds_write_b16_d16_hi v203, v23 offset:28016
	s_waitcnt vmcnt(3)
	ds_write_b16 v203, v24 offset:34816
	ds_write_b16_d16_hi v203, v24 offset:35088
	ds_write_b16 v203, v25 offset:35360
	ds_write_b16_d16_hi v203, v25 offset:35632
	ds_write_b16 v203, v26 offset:35904
	ds_write_b16_d16_hi v203, v26 offset:36176
	ds_write_b16 v203, v27 offset:36448
	ds_write_b16_d16_hi v203, v27 offset:36720
	s_waitcnt vmcnt(2)
	ds_write_b16 v203, v28 offset:43520
	ds_write_b16_d16_hi v203, v28 offset:43792
	ds_write_b16 v203, v29 offset:44064
	ds_write_b16_d16_hi v203, v29 offset:44336
	ds_write_b16 v203, v30 offset:44608
	ds_write_b16_d16_hi v203, v30 offset:44880
	ds_write_b16 v203, v31 offset:45152
	ds_write_b16_d16_hi v203, v31 offset:45424
	s_waitcnt vmcnt(1)
	ds_write_b16 v203, v32 offset:52224
	ds_write_b16_d16_hi v203, v32 offset:52496
	ds_write_b16 v203, v33 offset:52768
	ds_write_b16_d16_hi v203, v33 offset:53040
	ds_write_b16 v203, v34 offset:53312
	ds_write_b16_d16_hi v203, v34 offset:53584
	ds_write_b16 v203, v35 offset:53856
	ds_write_b16_d16_hi v203, v35 offset:54128
	s_waitcnt vmcnt(0)
	ds_write_b16 v203, v36 offset:60928
	ds_write_b16_d16_hi v203, v36 offset:61200
	ds_write_b16 v203, v37 offset:61472
	ds_write_b16_d16_hi v203, v37 offset:61744
	ds_write_b16 v203, v38 offset:62016
	ds_write_b16_d16_hi v203, v38 offset:62288
	ds_write_b16 v203, v39 offset:62560
	ds_write_b16_d16_hi v203, v39 offset:62832
	s_waitcnt lgkmcnt(0)
	s_barrier
	ds_read_b128 v[80:83], v204
	ds_read_b128 v[76:79], v204 offset:64
	ds_read_b128 v[72:75], v204 offset:128
	ds_read_b128 v[68:71], v204 offset:192
	s_and_b32 s100, s42, 31
	s_cmp_eq_u32 s100, 0
	s_cbranch_scc1 .La3st_skip
	s_lshl_b32 s98, s42, 16
	s_add_u32 s98, s12, s98
	s_addc_u32 s99, s13, 0
	v_lshl_add_u64 v[222:223], s[98:99], 0, v[94:95]
	global_load_dwordx4 v[222:225], v[222:223], off
	v_lshl_add_u64 v[226:227], s[98:99], 0, v[96:97]
	global_load_dwordx4 v[226:229], v[226:227], off
	v_lshl_add_u64 v[230:231], s[98:99], 0, v[98:99]
	global_load_dwordx4 v[230:233], v[230:231], off
	v_lshl_add_u64 v[234:235], s[98:99], 0, v[100:101]
	global_load_dwordx4 v[234:237], v[234:235], off
	v_lshl_add_u64 v[238:239], s[98:99], 0, v[102:103]
	global_load_dwordx4 v[238:241], v[238:239], off
	v_lshl_add_u64 v[242:243], s[98:99], 0, v[104:105]
	global_load_dwordx4 v[242:245], v[242:243], off
	v_lshl_add_u64 v[246:247], s[98:99], 0, v[106:107]
	global_load_dwordx4 v[246:249], v[246:247], off
	v_lshl_add_u64 v[250:251], s[98:99], 0, v[108:109]
	global_load_dwordx4 v[250:253], v[250:251], off
